# meta projection moved behind the GEMM prologue's first LDS-DMA issues (its loads share their round trip) + split-phase barrier at the GLU->gate seam
# baseline (speedup 1.0000x reference)
; #define PG8_BAR __builtin_amdgcn_s_barrier()
; template <class Epi, class Sched, bool ALIGN_EPI = false, bool SP2 = false, bool F16 = false>
; __device__ __forceinline__ void gemm_phase(PG8_LAS unsigned char* lds, const Gemm g, const Sched& S, const Epi& E) {
;     ...
;     if constexpr (SP2) {
;         PG8_STAGE(PG8_SB(0, 0), cB, voffB); PG8_STAGE(PG8_SB(0, 1), cB + hstep, voffB); PG8_STAGE(PG8_SA(0, 0), cA, voffA); PG8_STAGE(PG8_SA(0, 1), cA + hstep, voffA);
;         if (wr == 1) PG8_BAR;
;         PG8_WAIT_V(2); PG8_BAR;
;         PG8_STAGE(PG8_SB(1, 0), cB + kstep, voffB); PG8_STAGE(PG8_SA(1, 0), cA + kstep, voffA); PG8_STAGE(PG8_SB(1, 1), cB + hstep + kstep, voffB);
;         PG8_WAIT_V(6); PG8_BAR;
; __device__ __forceinline__ void meta_proj(const Args& a, int wave, int lane) {
;     unsigned char* ws = a.ws;
;     const bf16* XB = (const bf16*)(ws + WS_XB); const bf16* W1t = (const bf16*)(ws + WS_W1); const float* rstdx = (const float*)(ws + WS_RSTDX);
;     for (int gw = blockIdx.x * NWAVES + wave; gw < 1536; gw += gridDim.x * NWAVES) {
;     const int n = 1024 + gw;
;     float wf[16];
;     { const u32x4 w0 = *(const u32x4*)(W1t + (size_t)n * DM + lane * 8), w1 = *(const u32x4*)(W1t + (size_t)n * DM + 512 + lane * 8);
;       const unsigned ww[8] = {w0.x, w0.y, w0.z, w0.w, w1.x, w1.y, w1.z, w1.w};
; #pragma unroll
;       for (int e = 0; e < 8; ++e) { wf[2 * e] = bf_lo(ww[e]); wf[2 * e + 1] = bf_hi(ww[e]); } }
;     float mine = 0.f;
; #pragma unroll
;     for (int r = 0; r < 16; ++r) {
;         const u32x4 x0 = *(const u32x4*)(XB + (size_t)(META_ROW + r) * DM + lane * 8), x1 = *(const u32x4*)(XB + (size_t)(META_ROW + r) * DM + 512 + lane * 8);
;         const unsigned xx[8] = {x0.x, x0.y, x0.z, x0.w, x1.x, x1.y, x1.z, x1.w};
;         float s = 0.f;
; #pragma unroll
;         for (int e = 0; e < 8; ++e) s += bf_lo(xx[e]) * wf[2 * e] + bf_hi(xx[e]) * wf[2 * e + 1];
;         s = wave_sum(s);
;         if (lane == r) mine = s;
;     }
;     if (lane < 16) {
;         const unsigned short o = (unsigned short)(cvt_pk(mine * rstdx[META_ROW + lane], 0.f) & 0xffffu);
;         const size_t row = META_ROW + lane;
;         if (n < 1280) ((bf16*)(ws + WS_K))[row * KVW + (n - 1024)] = o;
;         else if (n < 1536) ((bf16*)(ws + WS_V))[row * KVW + (n - 1280)] = o;
;         else ((bf16*)(ws + WS_U))[row * DM + (n - 1536)] = o;
;     }
;     }
; }
.LBB0_169:
	s_add_u32 s50, s58, 0x2c00000
	s_addc_u32 s51, s59, 0
	v_and_b32_e32 v0, 32, v224
	s_add_u32 s48, s58, 0x6e00000
	v_bitop3_b32 v225, v112, v0, 48 bitop3:0x6c
	v_lshrrev_b32_e32 v0, 5, v224
	v_lshrrev_b32_e32 v129, 1, v224
	s_addc_u32 s49, s59, 0
	v_bfe_u32 v236, v224, 2, 4
	v_and_b32_e32 v0, 4, v0
	s_waitcnt lgkmcnt(2)
	v_bfe_u32 v1, v224, 2, 2
	v_and_b32_e32 v160, 24, v129
	v_lshrrev_b32_e32 v141, 3, v224
	s_movk_i32 s0, 0x70
	s_add_u32 s4, s58, 0xaf00000
	v_or3_b32 v0, v0, v1, v160
	v_and_or_b32 v232, v141, s0, v236
	s_movk_i32 s0, 0x60
	v_add_u32_e32 v237, 0x2000, v112
	s_addc_u32 s5, s59, 0
	v_and_or_b32 v231, v141, s0, v0
	v_lshrrev_b32_e32 v1, 7, v237
	s_movk_i32 s0, 0xf0
	s_add_u32 s6, s58, 0xc000000
	v_and_or_b32 v234, v1, s0, v236
	s_movk_i32 s0, 0xe0
	s_addc_u32 s7, s59, 0
	v_and_or_b32 v233, v1, s0, v0
	v_lshlrev_b32_e32 v0, 6, v224
	s_add_u32 s52, s58, 0xd100000
	v_and_b32_e32 v226, 64, v224
	v_and_b32_e32 v239, 0x3c0, v0
	v_lshlrev_b32_e32 v0, 2, v224
	s_addc_u32 s53, s59, 0
	v_or_b32_e32 v230, v225, v226
	v_lshlrev_b32_e32 v228, 1, v160
	v_and_b32_e32 v240, 32, v0
	v_readfirstlane_b32 s1, v224
	v_lshl_or_b32 v162, v232, 11, v230
	v_lshl_or_b32 v164, v231, 11, v230
	v_lshl_or_b32 v166, v234, 11, v230
	v_lshl_or_b32 v168, v233, 11, v230
	v_and_b32_e32 v227, 15, v224
	s_cmpk_gt_i32 s2, 0x4ff
	v_bitop3_b32 v229, v228, v240, v239 bitop3:0x36
	s_cbranch_scc1 .LBB0_193
	s_ashr_i32 s31, s2, 31
	s_lshr_b32 s0, s31, 29
	s_add_i32 s0, s2, s0
	s_lshr_b32 s10, s1, 6
	s_ashr_i32 s8, s0, 3
	s_and_b32 s0, s0, -8
	s_lshr_b32 s12, s1, 8
	s_lshl_b32 s30, s10, 10
	s_sub_i32 s0, s2, s0
	s_cmp_lt_i32 s0, 0
	s_movk_i32 s34, 0xa1
	s_cselect_b32 s9, s34, 0xa0
	s_mul_i32 s0, s0, s9
	s_add_i32 s0, s0, s8
	s_mul_hi_i32 s8, s0, 0x66666667
	s_lshr_b32 s9, s8, 31
	s_ashr_i32 s8, s8, 5
	s_add_i32 s8, s8, s9
	s_lshl_b32 s9, s8, 3
	s_mulk_i32 s8, 0x50
	s_sub_i32 s8, s0, s8
	s_bfe_i32 s0, s8, 0x80000
	s_bfe_u32 s0, s0, 0x3000c
	s_add_i32 s11, s8, s0
	s_bfe_i32 s0, s11, 0x80000
	s_and_b32 s11, s11, 0xf8
	s_sub_i32 s8, s8, s11
	s_sext_i32_i16 s0, s0
	s_sext_i32_i8 s8, s8
	s_lshr_b32 s0, s0, 3
	s_add_i32 s22, s9, s8
	s_ashr_i32 s23, s22, 31
	s_bfe_i64 s[14:15], s[0:1], 0x100000
	s_lshl_b64 s[8:9], s[22:23], 19
	s_lshl_b64 s[14:15], s[14:15], 19
	s_add_u32 s26, s42, s14
	s_addc_u32 s27, s43, s15
	s_add_i32 s23, s30, 0
	s_add_i32 m0, s23, 0x10000
	v_mov_b32_e32 v165, 0
	global_load_lds_dwordx4 v164, s[26:27]
	s_add_i32 m0, s23, 0x12000
	s_add_u32 s14, s26, 0x40000
	global_load_lds_dwordx4 v168, s[26:27]
	s_addc_u32 s15, s27, 0
	s_add_i32 m0, s23, 0x14000
	v_mov_b32_e32 v169, v165
	global_load_lds_dwordx4 v164, s[14:15]
	s_add_i32 m0, s23, 0x16000
	s_add_u32 s24, s50, s8
	s_addc_u32 s25, s51, s9
	s_add_i32 s35, s23, 0x2000
	global_load_lds_dwordx4 v168, s[14:15]
	s_mov_b32 m0, s23
	s_add_u32 s8, s24, 0x40000
	global_load_lds_dwordx4 v162, s[24:25]
	s_mov_b32 m0, s35
	s_addc_u32 s9, s25, 0
	s_add_i32 s36, s23, 0x4000
	global_load_lds_dwordx4 v166, s[24:25]
	s_mov_b32 m0, s36
	s_add_i32 s37, s23, 0x6000
	global_load_lds_dwordx4 v162, s[8:9]
	s_mov_b32 m0, s37
	v_mov_b32_e32 v163, v165
	global_load_lds_dwordx4 v166, s[8:9]
	s_cmpk_gt_i32 s2, 0x5f
	s_cbranch_scc1 .Lmeta_done
	v_and_b32_e32 v0, 63, v224
	v_and_b32_e32 v1, 15, v0
	v_lshrrev_b32_e32 v2, 4, v0
	s_lshl_b32 s60, s33, 8
	v_lshl_add_u32 v4, v2, 4, s60
	v_lshl_add_u32 v5, v1, 11, v4
	s_add_u32 s62, s58, 0x6c00000
	s_addc_u32 s63, s59, 0
	s_lshl_b32 s64, s2, 15
	s_add_u32 s64, s64, 0x200000
	s_add_u32 s64, s42, s64
	s_addc_u32 s65, s43, 0
	global_load_dwordx4 v[8:11], v5, s[62:63]
	global_load_dwordx4 v[12:15], v5, s[62:63] offset:64
	global_load_dwordx4 v[16:19], v5, s[62:63] offset:128
	global_load_dwordx4 v[20:23], v5, s[62:63] offset:192
	global_load_dwordx4 v[24:27], v5, s[64:65]
	global_load_dwordx4 v[28:31], v5, s[64:65] offset:64
	global_load_dwordx4 v[32:35], v5, s[64:65] offset:128
	global_load_dwordx4 v[36:39], v5, s[64:65] offset:192
	v_lshlrev_b32_e32 v6, 4, v2
	v_add_u32_e32 v6, 0x20000, v6
	global_load_dwordx4 v[40:43], v6, s[58:59]
	s_lshl_b32 s61, s33, 10
	v_lshl_add_u32 v7, v0, 4, s61
	v_add_u32_e32 v7, 0x20000, v7
	s_waitcnt vmcnt(1)
	v_mfma_f32_16x16x32_bf16 v[44:47], v[8:11], v[24:27], 0
	v_mfma_f32_16x16x32_bf16 v[44:47], v[12:15], v[28:31], v[44:47]
	v_mfma_f32_16x16x32_bf16 v[44:47], v[16:19], v[32:35], v[44:47]
	v_mfma_f32_16x16x32_bf16 v[44:47], v[20:23], v[36:39], v[44:47]
	s_nop 11
	s_nop 3
	ds_write_b128 v7, v[44:47]
	s_waitcnt lgkmcnt(0)
	s_barrier
	s_cmp_lg_u32 s33, 0
	s_cbranch_scc1 .Lmeta_done
	v_lshlrev_b32_e32 v7, 4, v0
	v_add_u32_e32 v7, 0x20000, v7
	ds_read_b128 v[48:51], v7
	ds_read_b128 v[52:55], v7 offset:1024
	ds_read_b128 v[56:59], v7 offset:2048
	ds_read_b128 v[60:63], v7 offset:3072
	ds_read_b128 v[64:67], v7 offset:4096
	ds_read_b128 v[68:71], v7 offset:5120
	ds_read_b128 v[72:75], v7 offset:6144
	ds_read_b128 v[76:79], v7 offset:7168
	s_mov_b32 s66, 0xaf00000
	s_mov_b32 s67, 9
	s_mov_b32 s68, s2
	s_cmp_lt_u32 s2, 16
	s_cbranch_scc1 .Lmeta_reg
	s_mov_b32 s66, 0xc000000
	s_sub_u32 s68, s2, 16
	s_cmp_lt_u32 s2, 32
	s_cbranch_scc1 .Lmeta_reg
	s_mov_b32 s66, 0xd100000
	s_mov_b32 s67, 11
	s_sub_u32 s68, s2, 32
.Lmeta_reg:
	s_add_u32 s70, s58, s66
	s_addc_u32 s71, s59, 0
	s_lshl_b32 s68, s68, 5
	s_lshl_b32 s69, 1, s67
	v_lshlrev_b32_e32 v4, 2, v2
	v_add_u32_e32 v4, 0x8000, v4
	v_lshlrev_b32_e32 v4, s67, v4
	v_lshl_add_u32 v4, v1, 1, v4
	v_add_u32_e32 v4, s68, v4
	s_waitcnt lgkmcnt(0)
	v_pk_add_f32 v[48:49], v[48:49], v[52:53]
	v_pk_add_f32 v[50:51], v[50:51], v[54:55]
	v_pk_add_f32 v[48:49], v[48:49], v[56:57]
	v_pk_add_f32 v[50:51], v[50:51], v[58:59]
	v_pk_add_f32 v[48:49], v[48:49], v[60:61]
	v_pk_add_f32 v[50:51], v[50:51], v[62:63]
	v_pk_add_f32 v[48:49], v[48:49], v[64:65]
	v_pk_add_f32 v[50:51], v[50:51], v[66:67]
	v_pk_add_f32 v[48:49], v[48:49], v[68:69]
	v_pk_add_f32 v[50:51], v[50:51], v[70:71]
	v_pk_add_f32 v[48:49], v[48:49], v[72:73]
	v_pk_add_f32 v[50:51], v[50:51], v[74:75]
	v_pk_add_f32 v[48:49], v[48:49], v[76:77]
	v_pk_add_f32 v[50:51], v[50:51], v[78:79]
	s_waitcnt vmcnt(0)
	v_pk_mul_f32 v[48:49], v[48:49], v[40:41]
	v_pk_mul_f32 v[50:51], v[50:51], v[42:43]
	v_mov_b32_e32 v5, 0
	s_nop 0
	v_cvt_pk_bf16_f32 v52, v48, v5
	v_cvt_pk_bf16_f32 v53, v49, v5
	v_cvt_pk_bf16_f32 v54, v50, v5
	v_cvt_pk_bf16_f32 v55, v51, v5
	global_store_short v4, v52, s[70:71]
	v_add_u32_e32 v4, s69, v4
	global_store_short v4, v53, s[70:71]
	v_add_u32_e32 v4, s69, v4
	global_store_short v4, v54, s[70:71]
	v_add_u32_e32 v4, s69, v4
	global_store_short v4, v55, s[70:71]
.Lmeta_done:
	v_mov_b32_e32 v167, v165
	s_cmp_eq_u32 s12, 1
	s_mov_b32 s38, 0
	v_lshl_add_u64 v[6:7], s[26:27], 0, v[164:165]
	s_waitcnt lgkmcnt(0)
	v_lshl_add_u64 v[4:5], s[26:27], 0, v[168:169]
	v_lshl_add_u64 v[0:1], s[24:25], 0, v[162:163]
	s_cselect_b64 s[8:9], -1, 0
	s_cmp_lg_u32 s12, 1
	v_lshl_add_u64 v[2:3], s[24:25], 0, v[166:167]
	s_cbranch_scc1 .LBB0_172
	s_barrier
